# merge-GEMM epilogue: y rows of the next group prefetched one group ahead into spare VGPRs
# speedup vs baseline: 1.0314x; 1.0043x over previous
; #define PG8_STAGE(bufoff, gbase, voff) do { _Pragma("unroll") for (int _i = 0; _i < 2; ++_i) \
;         __builtin_amdgcn_global_load_lds((const unsigned*)((const char*)(gbase) + (voff)[_i]), (LAS unsigned*)(lds + (bufoff) + ldsw + _i * 8192), 16, 0, 0); } while (0)
; #define PG8_LDA(dst, b, h) do { _Pragma("unroll") for (int m = 0; m < 4; ++m) _Pragma("unroll") for (int k = 0; k < 2; ++k) dst[m][k] = *(const LAS bf16x8*)(lds + PG8_SA(b, h) + aoff + m * 2048 + k * 1024); } while (0)
; #define PG8_LDB(dst, b, h) do { _Pragma("unroll") for (int n = 0; n < 2; ++n) _Pragma("unroll") for (int k = 0; k < 2; ++k) dst[n][k] = *(const LAS bf16x8*)(lds + PG8_SB(b, h) + boff + n * 2048 + k * 1024); } while (0)
; #define PG8_MMA(ai, bj, At, Bt) do { __builtin_amdgcn_s_setprio(1); _Pragma("unroll") for (int m = 0; m < 4; ++m) _Pragma("unroll") for (int n = 0; n < 2; ++n) _Pragma("unroll") for (int k = 0; k < 2; ++k) \
;         acc[ai][bj][m][n] = __builtin_amdgcn_mfma_f32_16x16x32_bf16(Bt[n][k], At[m][k], acc[ai][bj][m][n], 0, 0, 0); __builtin_amdgcn_s_setprio(0); } while (0)
; #define PG8_WAIT_V(n) asm volatile("s_waitcnt vmcnt(" #n ")" ::: "memory")
; #define PG8_WAIT_L(n) asm volatile("s_waitcnt lgkmcnt(" #n ")" ::: "memory")
; #define PG8_BAR __builtin_amdgcn_s_barrier()
; #define PG8_SCHED __builtin_amdgcn_sched_barrier(0)
; template <class Epi, class Sched, bool AREMAP>
; __device__ __forceinline__ void gemm_phase(LAS unsigned char* lds, const Gemm g, const Sched& S, const Epi& E, int wv) {
;     ...
;             PG8_LDB(B0, 0, 0); PG8_SCHED; PG8_LDA(At, 0, 0); PG8_STAGE(PG8_SA(1, 1), a1 + hstepA, voffA);
;             PG8_WAIT_L(8); PG8_BAR; PG8_WAIT_L(0); PG8_MMA(0, 0, At, B0); PG8_BAR; PG8_SCHED;
;             PG8_LDB(B1, 0, 1); PG8_STAGE(PG8_SB(0, 0), b2, voffB);
;             PG8_BAR; PG8_WAIT_L(0); PG8_MMA(0, 1, At, B1); PG8_BAR;
;             PG8_LDA(At, 0, 1); PG8_STAGE(PG8_SA(0, 0), a2, voffA);
;             PG8_BAR; PG8_WAIT_L(0); PG8_MMA(1, 0, At, B0); PG8_BAR; PG8_SCHED;
;             PG8_STAGE(PG8_SB(0, 1), b2 + hstepB, voffB);
;             PG8_WAIT_V(6); PG8_BAR; PG8_MMA(1, 1, At, B1); PG8_BAR;
.LBB0_426:
	s_add_u32 s20, s18, 0xfff80080
	s_addc_u32 s21, s19, -1
	s_add_i32 s38, 0, 0x10000
	v_add_u32_e32 v142, s38, v186
	ds_read_b128 v[130:133], v142
	ds_read_b128 v[134:137], v142 offset:1024
	ds_read_b128 v[138:141], v142 offset:2048
	ds_read_b128 v[142:145], v142 offset:3072
	s_cmp_eq_u32 s46, 28
	s_cselect_b32 s23, s3, s21
	s_cselect_b32 s22, s5, s20
	s_cselect_b32 s21, s11, s37
	s_cselect_b32 s20, s13, s36
	v_lshl_add_u64 v[198:199], s[18:19], 0, v[172:173]
	s_add_i32 m0, s35, 0xc000
	ds_read_b128 v[146:149], v196
	ds_read_b128 v[150:153], v196 offset:1024
	ds_read_b128 v[154:157], v196 offset:2048
	ds_read_b128 v[158:161], v196 offset:3072
	ds_read_b128 v[174:177], v196 offset:4096
	ds_read_b128 v[178:181], v196 offset:5120
	ds_read_b128 v[182:185], v196 offset:6144
	ds_read_b128 v[192:195], v196 offset:7168
	global_load_lds_dwordx4 v[198:199], off
	v_lshl_add_u64 v[198:199], s[18:19], 0, v[170:171]
	s_add_i32 m0, s35, 0xe000
	s_nop 0
	global_load_lds_dwordx4 v[198:199], off
	s_waitcnt lgkmcnt(8)
	s_barrier
	s_waitcnt lgkmcnt(0)
	s_setprio 1
	s_waitcnt lgkmcnt(0)
	v_mfma_f32_16x16x32_bf16 v[126:129], v[130:133], v[146:149], v[126:129]
	v_mfma_f32_16x16x32_bf16 v[122:125], v[138:141], v[146:149], v[122:125]
	v_mfma_f32_16x16x32_bf16 v[110:113], v[130:133], v[154:157], v[110:113]
	v_mfma_f32_16x16x32_bf16 v[106:109], v[138:141], v[154:157], v[106:109]
	v_mfma_f32_16x16x32_bf16 v[94:97], v[130:133], v[174:177], v[94:97]
	v_mfma_f32_16x16x32_bf16 v[90:93], v[138:141], v[174:177], v[90:93]
	v_mfma_f32_16x16x32_bf16 v[78:81], v[130:133], v[182:185], v[78:81]
	v_mfma_f32_16x16x32_bf16 v[74:77], v[138:141], v[182:185], v[74:77]
	v_mfma_f32_16x16x32_bf16 v[126:129], v[134:137], v[150:153], v[126:129]
	v_mfma_f32_16x16x32_bf16 v[122:125], v[142:145], v[150:153], v[122:125]
	v_mfma_f32_16x16x32_bf16 v[110:113], v[134:137], v[158:161], v[110:113]
	v_mfma_f32_16x16x32_bf16 v[106:109], v[142:145], v[158:161], v[106:109]
	v_mfma_f32_16x16x32_bf16 v[94:97], v[134:137], v[178:181], v[94:97]
	v_mfma_f32_16x16x32_bf16 v[90:93], v[142:145], v[178:181], v[90:93]
	v_mfma_f32_16x16x32_bf16 v[78:81], v[134:137], v[192:195], v[78:81]
	v_mfma_f32_16x16x32_bf16 v[74:77], v[142:145], v[192:195], v[74:77]
	s_setprio 0
	s_barrier
	s_add_i32 s39, 0, 0x14000
	s_add_i32 s38, s38, s34
	v_add_u32_e32 v197, s39, v186
	v_lshl_add_u64 v[214:215], s[20:21], 0, v[164:165]
	s_mov_b32 m0, s38
	ds_read_b128 v[198:201], v197
	ds_read_b128 v[202:205], v197 offset:1024
	ds_read_b128 v[206:209], v197 offset:2048
	ds_read_b128 v[210:213], v197 offset:3072
	global_load_lds_dwordx4 v[214:215], off
	v_lshl_add_u64 v[216:217], s[20:21], 0, v[168:169]
	s_add_i32 m0, s38, 0x2000
	s_nop 0
	global_load_lds_dwordx4 v[216:217], off
	s_barrier
	s_waitcnt lgkmcnt(0)
	s_setprio 1
	s_waitcnt lgkmcnt(0)
	v_mfma_f32_16x16x32_bf16 v[118:121], v[198:201], v[146:149], v[118:121]
	v_mfma_f32_16x16x32_bf16 v[114:117], v[206:209], v[146:149], v[114:117]
	v_mfma_f32_16x16x32_bf16 v[102:105], v[198:201], v[154:157], v[102:105]
	v_mfma_f32_16x16x32_bf16 v[98:101], v[206:209], v[154:157], v[98:101]
	v_mfma_f32_16x16x32_bf16 v[86:89], v[198:201], v[174:177], v[86:89]
	v_mfma_f32_16x16x32_bf16 v[82:85], v[206:209], v[174:177], v[82:85]
	v_mfma_f32_16x16x32_bf16 v[70:73], v[198:201], v[182:185], v[70:73]
	v_mfma_f32_16x16x32_bf16 v[66:69], v[206:209], v[182:185], v[66:69]
	v_mfma_f32_16x16x32_bf16 v[118:121], v[202:205], v[150:153], v[118:121]
	v_mfma_f32_16x16x32_bf16 v[114:117], v[210:213], v[150:153], v[114:117]
	v_mfma_f32_16x16x32_bf16 v[102:105], v[202:205], v[158:161], v[102:105]
	v_mfma_f32_16x16x32_bf16 v[98:101], v[210:213], v[158:161], v[98:101]
	v_mfma_f32_16x16x32_bf16 v[86:89], v[202:205], v[178:181], v[86:89]
	v_mfma_f32_16x16x32_bf16 v[82:85], v[210:213], v[178:181], v[82:85]
	v_mfma_f32_16x16x32_bf16 v[70:73], v[202:205], v[192:195], v[70:73]
	v_mfma_f32_16x16x32_bf16 v[66:69], v[210:213], v[192:195], v[66:69]
	s_setprio 0
	s_mov_b32 m0, s35
	v_lshl_add_u64 v[218:219], s[22:23], 0, v[162:163]
	s_barrier
	ds_read_b128 v[146:149], v196 offset:16384
	ds_read_b128 v[150:153], v196 offset:17408
	ds_read_b128 v[154:157], v196 offset:18432
	ds_read_b128 v[158:161], v196 offset:19456
	ds_read_b128 v[174:177], v196 offset:20480
	ds_read_b128 v[178:181], v196 offset:21504
	ds_read_b128 v[182:185], v196 offset:22528
	ds_read_b128 v[192:195], v196 offset:23552
	global_load_lds_dwordx4 v[218:219], off
	v_lshl_add_u64 v[220:221], s[22:23], 0, v[166:167]
	s_mov_b32 m0, s41
	s_nop 0
	global_load_lds_dwordx4 v[220:221], off
	s_barrier
	s_waitcnt lgkmcnt(0)
	s_setprio 1
	s_waitcnt lgkmcnt(0)
	v_mfma_f32_16x16x32_bf16 v[62:65], v[130:133], v[146:149], v[62:65]
	v_mfma_f32_16x16x32_bf16 v[58:61], v[138:141], v[146:149], v[58:61]
	v_mfma_f32_16x16x32_bf16 v[46:49], v[130:133], v[154:157], v[46:49]
	v_mfma_f32_16x16x32_bf16 v[42:45], v[138:141], v[154:157], v[42:45]
	v_mfma_f32_16x16x32_bf16 v[30:33], v[130:133], v[174:177], v[30:33]
	v_mfma_f32_16x16x32_bf16 v[26:29], v[138:141], v[174:177], v[26:29]
	v_mfma_f32_16x16x32_bf16 v[14:17], v[130:133], v[182:185], v[14:17]
	v_mfma_f32_16x16x32_bf16 v[10:13], v[138:141], v[182:185], v[10:13]
	v_mfma_f32_16x16x32_bf16 v[62:65], v[134:137], v[150:153], v[62:65]
	v_mfma_f32_16x16x32_bf16 v[58:61], v[142:145], v[150:153], v[58:61]
	v_mfma_f32_16x16x32_bf16 v[46:49], v[134:137], v[158:161], v[46:49]
	v_mfma_f32_16x16x32_bf16 v[42:45], v[142:145], v[158:161], v[42:45]
	v_mfma_f32_16x16x32_bf16 v[30:33], v[134:137], v[178:181], v[30:33]
	v_mfma_f32_16x16x32_bf16 v[26:29], v[142:145], v[178:181], v[26:29]
	v_mfma_f32_16x16x32_bf16 v[14:17], v[134:137], v[192:195], v[14:17]
	v_mfma_f32_16x16x32_bf16 v[10:13], v[142:145], v[192:195], v[10:13]
	s_setprio 0
	s_barrier
; #define PG8_STAGE(bufoff, gbase, voff) do { _Pragma("unroll") for (int _i = 0; _i < 2; ++_i) \
;         __builtin_amdgcn_global_load_lds((const unsigned*)((const char*)(gbase) + (voff)[_i]), (LAS unsigned*)(lds + (bufoff) + ldsw + _i * 8192), 16, 0, 0); } while (0)
; #define PG8_LDA(dst, b, h) do { _Pragma("unroll") for (int m = 0; m < 4; ++m) _Pragma("unroll") for (int k = 0; k < 2; ++k) dst[m][k] = *(const LAS bf16x8*)(lds + PG8_SA(b, h) + aoff + m * 2048 + k * 1024); } while (0)
; #define PG8_LDB(dst, b, h) do { _Pragma("unroll") for (int n = 0; n < 2; ++n) _Pragma("unroll") for (int k = 0; k < 2; ++k) dst[n][k] = *(const LAS bf16x8*)(lds + PG8_SB(b, h) + boff + n * 2048 + k * 1024); } while (0)
; #define PG8_MMA(ai, bj, At, Bt) do { __builtin_amdgcn_s_setprio(1); _Pragma("unroll") for (int m = 0; m < 4; ++m) _Pragma("unroll") for (int n = 0; n < 2; ++n) _Pragma("unroll") for (int k = 0; k < 2; ++k) \
;         acc[ai][bj][m][n] = __builtin_amdgcn_mfma_f32_16x16x32_bf16(Bt[n][k], At[m][k], acc[ai][bj][m][n], 0, 0, 0); __builtin_amdgcn_s_setprio(0); } while (0)
; #define PG8_WAIT_V(n) asm volatile("s_waitcnt vmcnt(" #n ")" ::: "memory")
; #define PG8_WAIT_L(n) asm volatile("s_waitcnt lgkmcnt(" #n ")" ::: "memory")
; #define PG8_BAR __builtin_amdgcn_s_barrier()
; #define PG8_SCHED __builtin_amdgcn_sched_barrier(0)
; template <class Epi, class Sched, bool AREMAP>
; __device__ __forceinline__ void gemm_phase(LAS unsigned char* lds, const Gemm g, const Sched& S, const Epi& E, int wv) {
;     ...
;             PG8_WAIT_V(6); PG8_BAR; PG8_MMA(1, 1, At, B1); PG8_BAR;
;             PG8_LDB(B0, 1, 0); PG8_SCHED; PG8_LDA(At, 1, 0); PG8_STAGE(PG8_SA(0, 1), a2 + hstepA, voffA);
;             PG8_WAIT_L(8); PG8_BAR; PG8_WAIT_L(0); PG8_MMA(0, 0, At, B0); PG8_BAR; PG8_SCHED;
;             PG8_LDB(B1, 1, 1); PG8_STAGE(PG8_SB(1, 0), b3, voffB);
;             PG8_BAR; PG8_WAIT_L(0); PG8_MMA(0, 1, At, B1); PG8_BAR;
;             PG8_LDA(At, 1, 1); PG8_STAGE(PG8_SA(1, 0), a3, voffA);
;             PG8_BAR; PG8_WAIT_L(0); PG8_MMA(1, 0, At, B0); PG8_BAR; PG8_SCHED;
	s_add_u32 s66, s20, 0x80000
	s_addc_u32 s67, s21, 0
	s_add_i32 s38, s39, s34
	v_lshl_add_u64 v[130:131], s[66:67], 0, v[164:165]
	s_mov_b32 m0, s38
	s_nop 0
	global_load_lds_dwordx4 v[130:131], off
	v_lshl_add_u64 v[130:131], s[66:67], 0, v[168:169]
	s_add_i32 m0, s38, 0x2000
	s_nop 0
	global_load_lds_dwordx4 v[130:131], off
	s_waitcnt vmcnt(6)
	s_barrier
	s_setprio 1
	v_mfma_f32_16x16x32_bf16 v[54:57], v[198:201], v[146:149], v[54:57]
	v_mfma_f32_16x16x32_bf16 v[50:53], v[206:209], v[146:149], v[50:53]
	v_mfma_f32_16x16x32_bf16 v[38:41], v[198:201], v[154:157], v[38:41]
	v_mfma_f32_16x16x32_bf16 v[34:37], v[206:209], v[154:157], v[34:37]
	v_mfma_f32_16x16x32_bf16 v[22:25], v[198:201], v[174:177], v[22:25]
	v_mfma_f32_16x16x32_bf16 v[18:21], v[206:209], v[174:177], v[18:21]
	v_mfma_f32_16x16x32_bf16 v[6:9], v[198:201], v[182:185], v[6:9]
	v_mfma_f32_16x16x32_bf16 v[2:5], v[206:209], v[182:185], v[2:5]
	v_mfma_f32_16x16x32_bf16 v[54:57], v[202:205], v[150:153], v[54:57]
	v_mfma_f32_16x16x32_bf16 v[50:53], v[210:213], v[150:153], v[50:53]
	v_mfma_f32_16x16x32_bf16 v[38:41], v[202:205], v[158:161], v[38:41]
	v_mfma_f32_16x16x32_bf16 v[34:37], v[210:213], v[158:161], v[34:37]
	v_mfma_f32_16x16x32_bf16 v[22:25], v[202:205], v[178:181], v[22:25]
	v_mfma_f32_16x16x32_bf16 v[18:21], v[210:213], v[178:181], v[18:21]
	v_mfma_f32_16x16x32_bf16 v[6:9], v[202:205], v[192:195], v[6:9]
	v_mfma_f32_16x16x32_bf16 v[2:5], v[210:213], v[192:195], v[2:5]
	s_setprio 0
	s_add_i32 s38, 0, 0x18000
	v_add_u32_e32 v142, s38, v186
	s_barrier
	ds_read_b128 v[130:133], v142
	ds_read_b128 v[134:137], v142 offset:1024
	ds_read_b128 v[138:141], v142 offset:2048
	ds_read_b128 v[142:145], v142 offset:3072
	s_add_u32 s22, s22, 0x80000
	s_addc_u32 s23, s23, 0
	s_mov_b32 m0, s52
	v_lshl_add_u64 v[198:199], s[22:23], 0, v[162:163]
	ds_read_b128 v[146:149], v196 offset:32768
	ds_read_b128 v[150:153], v196 offset:33792
	ds_read_b128 v[154:157], v196 offset:34816
	ds_read_b128 v[158:161], v196 offset:35840
	ds_read_b128 v[174:177], v196 offset:36864
	ds_read_b128 v[178:181], v196 offset:37888
	ds_read_b128 v[182:185], v196 offset:38912
	ds_read_b128 v[192:195], v196 offset:39936
	global_load_lds_dwordx4 v[198:199], off
	v_lshl_add_u64 v[198:199], s[22:23], 0, v[166:167]
	s_mov_b32 m0, s53
	s_nop 0
	global_load_lds_dwordx4 v[198:199], off
	s_waitcnt lgkmcnt(8)
	s_barrier
	s_waitcnt lgkmcnt(0)
	s_setprio 1
	s_waitcnt lgkmcnt(0)
	v_mfma_f32_16x16x32_bf16 v[126:129], v[130:133], v[146:149], v[126:129]
	v_mfma_f32_16x16x32_bf16 v[122:125], v[138:141], v[146:149], v[122:125]
	v_mfma_f32_16x16x32_bf16 v[110:113], v[130:133], v[154:157], v[110:113]
	v_mfma_f32_16x16x32_bf16 v[106:109], v[138:141], v[154:157], v[106:109]
	v_mfma_f32_16x16x32_bf16 v[94:97], v[130:133], v[174:177], v[94:97]
	v_mfma_f32_16x16x32_bf16 v[90:93], v[138:141], v[174:177], v[90:93]
	v_mfma_f32_16x16x32_bf16 v[78:81], v[130:133], v[182:185], v[78:81]
	v_mfma_f32_16x16x32_bf16 v[74:77], v[138:141], v[182:185], v[74:77]
	v_mfma_f32_16x16x32_bf16 v[126:129], v[134:137], v[150:153], v[126:129]
	v_mfma_f32_16x16x32_bf16 v[122:125], v[142:145], v[150:153], v[122:125]
	v_mfma_f32_16x16x32_bf16 v[110:113], v[134:137], v[158:161], v[110:113]
	v_mfma_f32_16x16x32_bf16 v[106:109], v[142:145], v[158:161], v[106:109]
	v_mfma_f32_16x16x32_bf16 v[94:97], v[134:137], v[178:181], v[94:97]
	v_mfma_f32_16x16x32_bf16 v[90:93], v[142:145], v[178:181], v[90:93]
	v_mfma_f32_16x16x32_bf16 v[78:81], v[134:137], v[192:195], v[78:81]
	v_mfma_f32_16x16x32_bf16 v[74:77], v[142:145], v[192:195], v[74:77]
	s_setprio 0
	s_barrier
	s_add_i32 s22, 0, 0x1c000
	s_add_i32 s23, s38, s34
	v_add_u32_e32 v197, s22, v186
	v_lshl_add_u64 v[214:215], v[214:215], 0, s[86:87]
	s_mov_b32 m0, s23
	ds_read_b128 v[198:201], v197
	ds_read_b128 v[202:205], v197 offset:1024
	ds_read_b128 v[206:209], v197 offset:2048
	ds_read_b128 v[210:213], v197 offset:3072
	global_load_lds_dwordx4 v[214:215], off
	v_lshl_add_u64 v[214:215], v[216:217], 0, s[86:87]
	s_add_i32 m0, s23, 0x2000
	s_nop 0
	global_load_lds_dwordx4 v[214:215], off
	s_barrier
	s_waitcnt lgkmcnt(0)
	s_setprio 1
	s_waitcnt lgkmcnt(0)
	v_mfma_f32_16x16x32_bf16 v[118:121], v[198:201], v[146:149], v[118:121]
	v_mfma_f32_16x16x32_bf16 v[114:117], v[206:209], v[146:149], v[114:117]
	v_mfma_f32_16x16x32_bf16 v[102:105], v[198:201], v[154:157], v[102:105]
	v_mfma_f32_16x16x32_bf16 v[98:101], v[206:209], v[154:157], v[98:101]
	v_mfma_f32_16x16x32_bf16 v[86:89], v[198:201], v[174:177], v[86:89]
	v_mfma_f32_16x16x32_bf16 v[82:85], v[206:209], v[174:177], v[82:85]
	v_mfma_f32_16x16x32_bf16 v[70:73], v[198:201], v[182:185], v[70:73]
	v_mfma_f32_16x16x32_bf16 v[66:69], v[206:209], v[182:185], v[66:69]
	v_mfma_f32_16x16x32_bf16 v[118:121], v[202:205], v[150:153], v[118:121]
	v_mfma_f32_16x16x32_bf16 v[114:117], v[210:213], v[150:153], v[114:117]
	v_mfma_f32_16x16x32_bf16 v[102:105], v[202:205], v[158:161], v[102:105]
	v_mfma_f32_16x16x32_bf16 v[98:101], v[210:213], v[158:161], v[98:101]
	v_mfma_f32_16x16x32_bf16 v[86:89], v[202:205], v[178:181], v[86:89]
	v_mfma_f32_16x16x32_bf16 v[82:85], v[210:213], v[178:181], v[82:85]
	v_mfma_f32_16x16x32_bf16 v[70:73], v[202:205], v[192:195], v[70:73]
	v_mfma_f32_16x16x32_bf16 v[66:69], v[210:213], v[192:195], v[66:69]
	s_setprio 0
	s_mov_b32 m0, s57
	v_lshl_add_u64 v[214:215], v[218:219], 0, s[86:87]
	s_barrier
; __device__ __forceinline__ int otid(int wv) { int t = (wv << 6) | (int)__builtin_amdgcn_mbcnt_hi(~0u, __builtin_amdgcn_mbcnt_lo(~0u, 0u)); asm volatile("" : "+v"(t)); return t; }
; #define PG8_STAGE(bufoff, gbase, voff) do { _Pragma("unroll") for (int _i = 0; _i < 2; ++_i) \
;         __builtin_amdgcn_global_load_lds((const unsigned*)((const char*)(gbase) + (voff)[_i]), (LAS unsigned*)(lds + (bufoff) + ldsw + _i * 8192), 16, 0, 0); } while (0)
; #define PG8_LDA(dst, b, h) do { _Pragma("unroll") for (int m = 0; m < 4; ++m) _Pragma("unroll") for (int k = 0; k < 2; ++k) dst[m][k] = *(const LAS bf16x8*)(lds + PG8_SA(b, h) + aoff + m * 2048 + k * 1024); } while (0)
; #define PG8_LDB(dst, b, h) do { _Pragma("unroll") for (int n = 0; n < 2; ++n) _Pragma("unroll") for (int k = 0; k < 2; ++k) dst[n][k] = *(const LAS bf16x8*)(lds + PG8_SB(b, h) + boff + n * 2048 + k * 1024); } while (0)
; #define PG8_BAR __builtin_amdgcn_s_barrier()
; template <class Epi, class Sched, bool AREMAP>
; __device__ __forceinline__ void gemm_phase(LAS unsigned char* lds, const Gemm g, const Sched& S, const Epi& E, int wv) {
;     ...
;             PG8_LDB(B1, 1, 1); PG8_STAGE(PG8_SB(1, 0), b3, voffB);
;             PG8_BAR; PG8_WAIT_L(0); PG8_MMA(0, 1, At, B1); PG8_BAR;
;             PG8_LDA(At, 1, 1); PG8_STAGE(PG8_SA(1, 0), a3, voffA);
;             PG8_BAR; PG8_WAIT_L(0); PG8_MMA(1, 0, At, B0); PG8_BAR; PG8_SCHED;
;             PG8_STAGE(PG8_SB(1, 1), b3 + hstepB, voffB);
;             PG8_WAIT_V(6); PG8_BAR; PG8_MMA(1, 1, At, B1); PG8_BAR;
;     __device__ __forceinline__ void operator()(const f32x4 (&acc)[2][2][4][2], const Unit& u, int wr, int wc, int fr, int fq) const {
;         const int b = u.pn >> 3, pn8 = u.pn & 7;
;         const int row0 = u.pm * BM + wr * 64 + fr, col0 = pn8 * BM + wc * 32 + 8 * fq;
;         const bf16_t* yb = YB + (size_t)b * NTOK * DM;
;         u32x4* sc = (u32x4*)scratch + otid(wv);
; #pragma unroll
;         for (int ai = 0; ai < 2; ++ai)
; #pragma unroll
;             for (int mp = 0; mp < 2; ++mp) {
;                 u32x4 y[2][2], pr[2][2];
; #pragma unroll
;                 for (int mm = 0; mm < 2; ++mm)
; #pragma unroll
;                     for (int bj = 0; bj < 2; ++bj) { const int m = mp * 2 + mm; const size_t off = (size_t)(row0 + ai * HALF + m * 16) * DM + col0;
;                         y[mm][bj] = *(const u32x4*)(yb + off + bj * HALF);
	ds_read_b128 v[146:149], v196 offset:49152
	ds_read_b128 v[150:153], v196 offset:50176
	ds_read_b128 v[154:157], v196 offset:51200
	ds_read_b128 v[158:161], v196 offset:52224
	ds_read_b128 v[174:177], v196 offset:53248
	ds_read_b128 v[178:181], v196 offset:54272
	ds_read_b128 v[182:185], v196 offset:55296
	ds_read_b128 v[192:195], v196 offset:56320
	global_load_lds_dwordx4 v[214:215], off
	v_lshl_add_u64 v[214:215], v[220:221], 0, s[86:87]
	s_mov_b32 m0, s62
	s_nop 0
	global_load_lds_dwordx4 v[214:215], off
	s_barrier
	s_waitcnt lgkmcnt(0)
	s_setprio 1
	s_waitcnt lgkmcnt(0)
	v_mfma_f32_16x16x32_bf16 v[62:65], v[130:133], v[146:149], v[62:65]
	v_mfma_f32_16x16x32_bf16 v[58:61], v[138:141], v[146:149], v[58:61]
	v_mfma_f32_16x16x32_bf16 v[46:49], v[130:133], v[154:157], v[46:49]
	v_mfma_f32_16x16x32_bf16 v[42:45], v[138:141], v[154:157], v[42:45]
	v_mfma_f32_16x16x32_bf16 v[30:33], v[130:133], v[174:177], v[30:33]
	v_mfma_f32_16x16x32_bf16 v[26:29], v[138:141], v[174:177], v[26:29]
	v_mfma_f32_16x16x32_bf16 v[14:17], v[130:133], v[182:185], v[14:17]
	v_mfma_f32_16x16x32_bf16 v[10:13], v[138:141], v[182:185], v[10:13]
	v_mfma_f32_16x16x32_bf16 v[62:65], v[134:137], v[150:153], v[62:65]
	v_mfma_f32_16x16x32_bf16 v[58:61], v[142:145], v[150:153], v[58:61]
	v_mfma_f32_16x16x32_bf16 v[46:49], v[134:137], v[158:161], v[46:49]
	v_mfma_f32_16x16x32_bf16 v[42:45], v[142:145], v[158:161], v[42:45]
	v_mfma_f32_16x16x32_bf16 v[30:33], v[134:137], v[178:181], v[30:33]
	v_mfma_f32_16x16x32_bf16 v[26:29], v[142:145], v[178:181], v[26:29]
	v_mfma_f32_16x16x32_bf16 v[14:17], v[134:137], v[192:195], v[14:17]
	v_mfma_f32_16x16x32_bf16 v[10:13], v[142:145], v[192:195], v[10:13]
	s_setprio 0
	s_barrier
	s_add_u32 s20, s20, 0x80080
	s_addc_u32 s21, s21, 0
	s_add_i32 s22, s22, s34
	v_lshl_add_u64 v[130:131], s[20:21], 0, v[164:165]
	s_mov_b32 m0, s22
	s_nop 0
	global_load_lds_dwordx4 v[130:131], off
	v_lshl_add_u64 v[130:131], s[20:21], 0, v[168:169]
	s_add_i32 m0, s22, 0x2000
	s_nop 0
	global_load_lds_dwordx4 v[130:131], off
	s_waitcnt vmcnt(6)
	s_barrier
	s_setprio 1
	v_mfma_f32_16x16x32_bf16 v[54:57], v[198:201], v[146:149], v[54:57]
	v_mfma_f32_16x16x32_bf16 v[50:53], v[206:209], v[146:149], v[50:53]
	v_mfma_f32_16x16x32_bf16 v[38:41], v[198:201], v[154:157], v[38:41]
	v_mfma_f32_16x16x32_bf16 v[34:37], v[206:209], v[154:157], v[34:37]
	v_mfma_f32_16x16x32_bf16 v[22:25], v[198:201], v[174:177], v[22:25]
	v_mfma_f32_16x16x32_bf16 v[18:21], v[206:209], v[174:177], v[18:21]
	v_mfma_f32_16x16x32_bf16 v[6:9], v[198:201], v[182:185], v[6:9]
	v_mfma_f32_16x16x32_bf16 v[2:5], v[206:209], v[182:185], v[2:5]
	v_mfma_f32_16x16x32_bf16 v[54:57], v[202:205], v[150:153], v[54:57]
	v_mfma_f32_16x16x32_bf16 v[50:53], v[210:213], v[150:153], v[50:53]
	v_mfma_f32_16x16x32_bf16 v[38:41], v[202:205], v[158:161], v[38:41]
	v_mfma_f32_16x16x32_bf16 v[34:37], v[210:213], v[158:161], v[34:37]
	v_mfma_f32_16x16x32_bf16 v[22:25], v[202:205], v[178:181], v[22:25]
	v_mfma_f32_16x16x32_bf16 v[18:21], v[210:213], v[178:181], v[18:21]
	v_mfma_f32_16x16x32_bf16 v[6:9], v[202:205], v[192:195], v[6:9]
	v_mfma_f32_16x16x32_bf16 v[2:5], v[210:213], v[192:195], v[2:5]
	s_setprio 0
	s_add_i32 s46, s46, 2
	s_add_u32 s36, s36, 0x100
	s_addc_u32 s37, s37, 0
	s_add_u32 s18, s18, 0x100
	s_addc_u32 s19, s19, 0
	s_cmp_gt_u32 s46, 29
	s_barrier
	s_cbranch_scc0 .LBB0_426
	s_ashr_i32 s18, s4, 3
	v_lshl_add_u32 v178, s2, 8, v1
	s_lshl_b32 s2, s4, 8
	s_and_b32 s2, s2, 0x700
	s_ashr_i32 s19, s18, 31
	v_or_b32_e32 v132, s2, v187
	s_lshl_b64 s[2:3], s[18:19], 27
	s_add_u32 s2, s55, s2
	s_addc_u32 s3, s56, s3
	v_mov_b32_e32 v130, v236
	v_lshlrev_b32_e32 v176, 1, v132
	v_mov_b32_e32 v177, v0
	v_ashrrev_i32_e32 v179, 31, v178
	v_lshl_add_u64 v[180:181], s[2:3], 0, v[176:177]
	v_ashrrev_i32_e32 v131, 31, v130
	v_lshlrev_b64 v[184:185], 12, v[178:179]
	v_lshl_add_u64 v[174:175], v[130:131], 4, s[6:7]
	v_lshl_add_u64 v[130:131], v[180:181], 0, v[184:185]
	v_mov_b64_e32 v[250:251], v[130:131]
	s_mov_b32 s20, 0x20000
	s_mov_b32 s21, 0
	v_lshl_add_u64 v[252:253], v[250:251], 0, s[20:21]
	global_load_dwordx4 v[198:201], v[252:253], off
	global_load_dwordx4 v[202:205], v[252:253], off offset:256
	s_mov_b32 s20, 0x30000
	v_lshl_add_u64 v[252:253], v[250:251], 0, s[20:21]
	global_load_dwordx4 v[206:209], v[252:253], off
	global_load_dwordx4 v[210:213], v[252:253], off offset:256
	global_load_dwordx4 v[154:157], v[130:131], off
	s_cmp_gt_i32 s18, 0
	s_cselect_b64 s[2:3], -1, 0
	s_cmp_lt_i32 s18, 1
	s_cbranch_scc1 .LBB0_429
	global_load_dwordx4 v[158:161], v[174:175], off
	s_branch .LBB0_430

; __device__ __forceinline__ unsigned cvt_pk_bf16(float lo, float hi) { f32x2_t f = {lo, hi}; bf16x2_t v = __builtin_convertvector(f, bf16x2_t); return __builtin_bit_cast(unsigned, v); }
; __device__ __forceinline__ float bflo(unsigned w) { return __uint_as_float(w << 16); }
; __device__ __forceinline__ float bfhi(unsigned w) { return __uint_as_float(w & 0xffff0000u); }
; __device__ __forceinline__ float sigmoidf_(float x) { return __builtin_amdgcn_rcpf(1.0f + __expf(-x)); }
;     __device__ __forceinline__ void operator()(const f32x4 (&acc)[2][2][4][2], const Unit& u, int wr, int wc, int fr, int fq) const {
;     ...
;                     for (int bj = 0; bj < 2; ++bj) { const int m = mp * 2 + mm; const size_t off = (size_t)(row0 + ai * HALF + m * 16) * DM + col0;
;                         const u32x4 yy = y[mm][bj], pp = pr[mm][bj];
;                         const f32x4 a0 = acc[ai][bj][m][0], a1 = acc[ai][bj][m][1];
;                         f32x4 r0, r1;
;                         r0[0] = bflo(pp.x) + sigmoidf_(a0[0]) * bflo(yy.x); r0[1] = bfhi(pp.x) + sigmoidf_(a0[1]) * bfhi(yy.x); r0[2] = bflo(pp.y) + sigmoidf_(a0[2]) * bflo(yy.y); r0[3] = bfhi(pp.y) + sigmoidf_(a0[3]) * bfhi(yy.y);
;                         r1[0] = bflo(pp.z) + sigmoidf_(a1[0]) * bflo(yy.z); r1[1] = bfhi(pp.z) + sigmoidf_(a1[1]) * bfhi(yy.z); r1[2] = bflo(pp.w) + sigmoidf_(a1[2]) * bflo(yy.w); r1[3] = bfhi(pp.w) + sigmoidf_(a1[3]) * bfhi(yy.w);
;                         u32x4 w; w.x = cvt_pk_bf16(r0[0], r0[1]); w.y = cvt_pk_bf16(r0[2], r0[3]); w.z = cvt_pk_bf16(r1[0], r1[1]); w.w = cvt_pk_bf16(r1[2], r1[3]);
;                         const int slot = (ai * 4 + m) * 2 + bj;
;                         if (b < 2) sc[(size_t)slot * NTHR] = w;
;                         else *(u32x4*)(merged + off + bj * HALF) = w; }
.LBB0_437:
	v_mul_f32_e32 v128, 0xbfb8aa3b, v128
	v_mul_f32_e32 v129, 0xbfb8aa3b, v129
	v_exp_f32_e32 v128, v128
	v_exp_f32_e32 v129, v129
	v_mul_f32_e32 v122, 0xbfb8aa3b, v122
	v_mul_f32_e32 v123, 0xbfb8aa3b, v123
	v_add_f32_e32 v128, 1.0, v128
	v_add_f32_e32 v129, 1.0, v129
	v_rcp_f32_e32 v128, v128
	v_rcp_f32_e32 v129, v129
	v_exp_f32_e32 v122, v122
	v_exp_f32_e32 v123, v123
	s_waitcnt vmcnt(0) lgkmcnt(0)
	s_mov_b32 s20, 0x80000
	s_mov_b32 s21, 0
	v_lshl_add_u64 v[252:253], v[250:251], 0, s[20:21]
	global_load_dwordx4 v[214:217], v[252:253], off
	global_load_dwordx4 v[222:225], v[252:253], off offset:256
	s_mov_b32 s20, 0x90000
	v_lshl_add_u64 v[252:253], v[250:251], 0, s[20:21]
	global_load_dwordx4 v[228:231], v[252:253], off
	global_load_dwordx4 v[232:235], v[252:253], off offset:256
	v_lshlrev_b32_e32 v192, 16, v158
	v_and_b32_e32 v193, 0xffff0000, v158
	v_lshlrev_b32_e32 v194, 16, v154
	v_and_b32_e32 v195, 0xffff0000, v154
	v_lshlrev_b32_e32 v158, 16, v159
	v_and_b32_e32 v159, 0xffff0000, v159
	v_lshlrev_b32_e32 v154, 16, v155
	v_and_b32_e32 v155, 0xffff0000, v155
	v_mul_f32_e32 v124, 0xbfb8aa3b, v124
	v_mul_f32_e32 v126, 0xbfb8aa3b, v126
	v_mul_f32_e32 v127, 0xbfb8aa3b, v127
	v_pk_fma_f32 v[128:129], v[128:129], v[154:155], v[158:159]
	v_add_f32_e32 v122, 1.0, v122
	v_add_f32_e32 v123, 1.0, v123
	v_lshlrev_b32_e32 v158, 16, v156
	v_and_b32_e32 v159, 0xffff0000, v156
	v_exp_f32_e32 v156, v124
	v_mul_f32_e32 v124, 0xbfb8aa3b, v125
	v_exp_f32_e32 v126, v126
	v_exp_f32_e32 v127, v127
	v_rcp_f32_e32 v122, v122
	v_rcp_f32_e32 v123, v123
	v_lshlrev_b32_e32 v154, 16, v160
	v_and_b32_e32 v155, 0xffff0000, v160
	v_exp_f32_e32 v160, v124
	v_add_f32_e32 v126, 1.0, v126
	v_add_f32_e32 v127, 1.0, v127
	v_pk_fma_f32 v[124:125], v[122:123], v[158:159], v[154:155]
	v_add_f32_e32 v122, 1.0, v156
	v_add_f32_e32 v123, 1.0, v160
	v_rcp_f32_e32 v126, v126
	v_rcp_f32_e32 v127, v127
	v_rcp_f32_e32 v122, v122
	v_rcp_f32_e32 v123, v123
	s_cmp_gt_i32 s18, 1
	v_lshlrev_b32_e32 v154, 16, v161
	v_and_b32_e32 v155, 0xffff0000, v161
	v_lshlrev_b32_e32 v156, 16, v157
	v_and_b32_e32 v157, 0xffff0000, v157
	s_cselect_b64 s[18:19], -1, 0
	v_pk_fma_f32 v[126:127], v[126:127], v[194:195], v[192:193]
	v_pk_fma_f32 v[154:155], v[122:123], v[156:157], v[154:155]
	v_cvt_pk_bf16_f32 v122, v126, v127
	v_cvt_pk_bf16_f32 v123, v128, v129
	v_cvt_pk_bf16_f32 v124, v124, v125
	v_cvt_pk_bf16_f32 v125, v154, v155
	s_mov_b64 s[2:3], -1
	s_and_b64 vcc, exec, s[18:19]
	v_lshl_add_u64 v[126:127], s[8:9], 0, v[184:185]
	s_cbranch_vccz .LBB0_439
	v_mov_b32_e32 v177, v0
	v_lshl_add_u64 v[128:129], v[126:127], 0, v[176:177]
	global_store_dwordx4 v[128:129], v[122:125], off
	s_mov_b64 s[2:3], 0

; __device__ __forceinline__ unsigned cvt_pk_bf16(float lo, float hi) { f32x2_t f = {lo, hi}; bf16x2_t v = __builtin_convertvector(f, bf16x2_t); return __builtin_bit_cast(unsigned, v); }
; __device__ __forceinline__ float bflo(unsigned w) { return __uint_as_float(w << 16); }
; __device__ __forceinline__ float bfhi(unsigned w) { return __uint_as_float(w & 0xffff0000u); }
; __device__ __forceinline__ float sigmoidf_(float x) { return __builtin_amdgcn_rcpf(1.0f + __expf(-x)); }
;     __device__ __forceinline__ void operator()(const f32x4 (&acc)[2][2][4][2], const Unit& u, int wr, int wc, int fr, int fq) const {
;     ...
;                     for (int bj = 0; bj < 2; ++bj) { const int m = mp * 2 + mm; const size_t off = (size_t)(row0 + ai * HALF + m * 16) * DM + col0;
;                         y[mm][bj] = *(const u32x4*)(yb + off + bj * HALF);
;                         const int slot = (ai * 4 + m) * 2 + bj;
;                         pr[mm][bj] = (u32x4){0u, 0u, 0u, 0u};
;                         if (b > 0) pr[mm][bj] = sc[(size_t)slot * NTHR]; }
; #pragma unroll
;                 for (int mm = 0; mm < 2; ++mm)
; #pragma unroll
;                     for (int bj = 0; bj < 2; ++bj) { const int m = mp * 2 + mm; const size_t off = (size_t)(row0 + ai * HALF + m * 16) * DM + col0;
;                         const u32x4 yy = y[mm][bj], pp = pr[mm][bj];
;                         const f32x4 a0 = acc[ai][bj][m][0], a1 = acc[ai][bj][m][1];
;                         f32x4 r0, r1;
;                         r0[0] = bflo(pp.x) + sigmoidf_(a0[0]) * bflo(yy.x); r0[1] = bfhi(pp.x) + sigmoidf_(a0[1]) * bfhi(yy.x); r0[2] = bflo(pp.y) + sigmoidf_(a0[2]) * bflo(yy.y); r0[3] = bfhi(pp.y) + sigmoidf_(a0[3]) * bfhi(yy.y);
;                         r1[0] = bflo(pp.z) + sigmoidf_(a1[0]) * bflo(yy.z); r1[1] = bfhi(pp.z) + sigmoidf_(a1[1]) * bfhi(yy.z); r1[2] = bflo(pp.w) + sigmoidf_(a1[2]) * bflo(yy.w); r1[3] = bfhi(pp.w) + sigmoidf_(a1[3]) * bfhi(yy.w);
;                         u32x4 w; w.x = cvt_pk_bf16(r0[0], r0[1]); w.y = cvt_pk_bf16(r0[2], r0[3]); w.z = cvt_pk_bf16(r1[0], r1[1]); w.w = cvt_pk_bf16(r1[2], r1[3]);
;                         const int slot = (ai * 4 + m) * 2 + bj;
;                         if (b < 2) sc[(size_t)slot * NTHR] = w;
;                         else *(u32x4*)(merged + off + bj * HALF) = w; }
.LBB0_453:
	s_nop 1
	v_or_b32_e32 v98, 32, v178
	v_ashrrev_i32_e32 v99, 31, v98
	v_lshlrev_b64 v[132:133], 12, v[98:99]
	v_lshl_add_u64 v[98:99], v[180:181], 0, v[132:133]
	v_mov_b64_e32 v[122:123], v[198:199]
	v_mov_b64_e32 v[124:125], v[200:201]
	v_mov_b32_e32 v114, 0
	s_and_b64 vcc, exec, s[4:5]
	v_mov_b32_e32 v126, 0
	v_mov_b32_e32 v127, 0
	v_mov_b32_e32 v128, 0
	v_mov_b32_e32 v129, 0
	s_cbranch_vccnz .LBB0_455
	v_add_co_u32_e32 v100, vcc, 0x8000, v174
	s_nop 1
	v_addc_co_u32_e32 v101, vcc, 0, v175, vcc
	global_load_dwordx4 v[126:129], v[100:101], off
.LBB0_455:
	v_mov_b64_e32 v[118:119], v[202:203]
	v_mov_b64_e32 v[120:121], v[204:205]
	s_and_b64 vcc, exec, s[4:5]
	v_mov_b32_e32 v115, 0
	v_mov_b32_e32 v116, 0
	v_mov_b32_e32 v117, 0
	s_cbranch_vccnz .LBB0_457
	v_add_co_u32_e32 v98, vcc, 0xa000, v174
	s_nop 1
	v_addc_co_u32_e32 v99, vcc, 0, v175, vcc
	global_load_dwordx4 v[114:117], v[98:99], off
.LBB0_457:
	v_or_b32_e32 v98, 48, v178
	v_ashrrev_i32_e32 v99, 31, v98
	v_lshlrev_b64 v[130:131], 12, v[98:99]
	v_lshl_add_u64 v[100:101], v[180:181], 0, v[130:131]
	v_mov_b64_e32 v[106:107], v[206:207]
	v_mov_b64_e32 v[108:109], v[208:209]
	v_mov_b32_e32 v98, 0
	s_and_b64 vcc, exec, s[4:5]
	v_mov_b32_e32 v110, 0
	v_mov_b32_e32 v111, 0
	v_mov_b32_e32 v112, 0
	v_mov_b32_e32 v113, 0
	s_cbranch_vccnz .LBB0_459
	v_add_co_u32_e32 v102, vcc, 0xc000, v174
	s_nop 1
	v_addc_co_u32_e32 v103, vcc, 0, v175, vcc
	global_load_dwordx4 v[110:113], v[102:103], off
.LBB0_459:
	s_nop 0
	v_mov_b64_e32 v[102:103], v[210:211]
	v_mov_b64_e32 v[104:105], v[212:213]
	s_and_b64 vcc, exec, s[4:5]
	v_mov_b32_e32 v99, 0
	v_mov_b32_e32 v100, 0
	v_mov_b32_e32 v101, 0
	s_cbranch_vccnz .LBB0_461
	v_add_co_u32_e32 v98, vcc, 0xe000, v174
	s_nop 1
	v_addc_co_u32_e32 v99, vcc, 0, v175, vcc
	global_load_dwordx4 v[98:101], v[98:99], off
.LBB0_461:
	v_mul_f32_e32 v96, 0xbfb8aa3b, v96
	v_mul_f32_e32 v97, 0xbfb8aa3b, v97
	v_exp_f32_e32 v96, v96
	v_exp_f32_e32 v97, v97
	v_mul_f32_e32 v90, 0xbfb8aa3b, v90
	v_mul_f32_e32 v91, 0xbfb8aa3b, v91
	v_add_f32_e32 v96, 1.0, v96
	v_add_f32_e32 v97, 1.0, v97
	v_rcp_f32_e32 v96, v96
	v_rcp_f32_e32 v97, v97
	v_exp_f32_e32 v90, v90
	v_exp_f32_e32 v91, v91
	s_waitcnt vmcnt(0) lgkmcnt(0)
	s_mov_b32 s20, 0xa0000
	s_mov_b32 s21, 0
	v_lshl_add_u64 v[252:253], v[250:251], 0, s[20:21]
	global_load_dwordx4 v[198:201], v[252:253], off
	global_load_dwordx4 v[202:205], v[252:253], off offset:256
	s_mov_b32 s20, 0xb0000
	v_lshl_add_u64 v[252:253], v[250:251], 0, s[20:21]
	global_load_dwordx4 v[206:209], v[252:253], off
	global_load_dwordx4 v[210:213], v[252:253], off offset:256
	v_lshlrev_b32_e32 v134, 16, v126
	v_and_b32_e32 v135, 0xffff0000, v126
	v_lshlrev_b32_e32 v136, 16, v122
	v_and_b32_e32 v137, 0xffff0000, v122
	v_lshlrev_b32_e32 v126, 16, v127
	v_and_b32_e32 v127, 0xffff0000, v127
	v_lshlrev_b32_e32 v122, 16, v123
	v_and_b32_e32 v123, 0xffff0000, v123
	v_mul_f32_e32 v92, 0xbfb8aa3b, v92
	v_mul_f32_e32 v94, 0xbfb8aa3b, v94
	v_mul_f32_e32 v95, 0xbfb8aa3b, v95
	v_pk_fma_f32 v[96:97], v[96:97], v[122:123], v[126:127]
	v_add_f32_e32 v90, 1.0, v90
	v_add_f32_e32 v91, 1.0, v91
	v_lshlrev_b32_e32 v126, 16, v124
	v_and_b32_e32 v127, 0xffff0000, v124
	v_exp_f32_e32 v124, v92
	v_mul_f32_e32 v92, 0xbfb8aa3b, v93
	v_exp_f32_e32 v94, v94
	v_exp_f32_e32 v95, v95
	v_rcp_f32_e32 v90, v90
	v_rcp_f32_e32 v91, v91
	v_lshlrev_b32_e32 v122, 16, v128
	v_and_b32_e32 v123, 0xffff0000, v128
	v_exp_f32_e32 v128, v92
	v_add_f32_e32 v94, 1.0, v94
	v_add_f32_e32 v95, 1.0, v95
	v_pk_fma_f32 v[92:93], v[90:91], v[126:127], v[122:123]
	v_add_f32_e32 v90, 1.0, v124
	v_add_f32_e32 v91, 1.0, v128
	v_rcp_f32_e32 v94, v94
	v_rcp_f32_e32 v95, v95
	v_rcp_f32_e32 v90, v90
	v_rcp_f32_e32 v91, v91
	v_lshlrev_b32_e32 v122, 16, v129
	v_and_b32_e32 v123, 0xffff0000, v129
	v_lshlrev_b32_e32 v124, 16, v125
	v_and_b32_e32 v125, 0xffff0000, v125
	v_pk_fma_f32 v[94:95], v[94:95], v[136:137], v[134:135]
	v_pk_fma_f32 v[122:123], v[90:91], v[124:125], v[122:123]
	v_cvt_pk_bf16_f32 v90, v94, v95
	v_cvt_pk_bf16_f32 v91, v96, v97
	v_cvt_pk_bf16_f32 v92, v92, v93
	v_cvt_pk_bf16_f32 v93, v122, v123
	s_mov_b64 s[18:19], -1
	s_and_b64 vcc, exec, s[2:3]
	v_lshl_add_u64 v[94:95], s[8:9], 0, v[132:133]
	s_cbranch_vccnz .LBB0_463
	v_mov_b32_e32 v177, v0
	v_lshl_add_u64 v[96:97], v[94:95], 0, v[176:177]
	s_mov_b64 s[18:19], 0
	global_store_dwordx4 v[96:97], v[90:93], off

;     __device__ __forceinline__ void operator()(const f32x4 (&acc)[2][2][4][2], const Unit& u, int wr, int wc, int fr, int fq) const {
;     ...
;                     for (int bj = 0; bj < 2; ++bj) { const int m = mp * 2 + mm; const size_t off = (size_t)(row0 + ai * HALF + m * 16) * DM + col0;
;                         y[mm][bj] = *(const u32x4*)(yb + off + bj * HALF);
;                         const int slot = (ai * 4 + m) * 2 + bj;
;                         pr[mm][bj] = (u32x4){0u, 0u, 0u, 0u};
;                         if (b > 0) pr[mm][bj] = sc[(size_t)slot * NTHR]; }
.LBB0_477:
	s_nop 1
	v_lshlrev_b64 v[66:67], 12, v[178:179]
	s_mov_b64 s[18:19], 0x80000
	v_lshl_add_u64 v[100:101], v[66:67], 0, s[18:19]
	v_lshl_add_u64 v[66:67], v[180:181], 0, v[100:101]
	v_mov_b64_e32 v[90:91], v[214:215]
	v_mov_b64_e32 v[92:93], v[216:217]
	v_mov_b32_e32 v82, 0
	s_and_b64 vcc, exec, s[4:5]
	v_mov_b32_e32 v94, 0
	v_mov_b32_e32 v95, 0
	v_mov_b32_e32 v96, 0
	v_mov_b32_e32 v97, 0
	s_cbranch_vccnz .LBB0_479
	v_add_co_u32_e32 v68, vcc, 0x10000, v174
	s_nop 1
	v_addc_co_u32_e32 v69, vcc, 0, v175, vcc
	global_load_dwordx4 v[94:97], v[68:69], off
.LBB0_479:
	v_mov_b64_e32 v[86:87], v[222:223]
	v_mov_b64_e32 v[88:89], v[224:225]
	s_and_b64 vcc, exec, s[4:5]
	v_mov_b32_e32 v83, 0
	v_mov_b32_e32 v84, 0
	v_mov_b32_e32 v85, 0
	s_cbranch_vccnz .LBB0_481
	v_add_co_u32_e32 v66, vcc, 0x12000, v174
	s_nop 1
	v_addc_co_u32_e32 v67, vcc, 0, v175, vcc
	global_load_dwordx4 v[82:85], v[66:67], off
.LBB0_481:
	v_lshlrev_b64 v[66:67], 12, v[178:179]
	s_mov_b64 s[18:19], 0x90000
	v_lshl_add_u64 v[98:99], v[66:67], 0, s[18:19]
	v_lshl_add_u64 v[68:69], v[180:181], 0, v[98:99]
	v_mov_b64_e32 v[74:75], v[228:229]
	v_mov_b64_e32 v[76:77], v[230:231]
	v_mov_b32_e32 v66, 0
	s_and_b64 vcc, exec, s[4:5]
	v_mov_b32_e32 v78, 0
	v_mov_b32_e32 v79, 0
	v_mov_b32_e32 v80, 0
	v_mov_b32_e32 v81, 0
	s_cbranch_vccnz .LBB0_483
	v_add_co_u32_e32 v70, vcc, 0x14000, v174
	s_nop 1
	v_addc_co_u32_e32 v71, vcc, 0, v175, vcc
	global_load_dwordx4 v[78:81], v[70:71], off
.LBB0_483:
	s_nop 0
	v_mov_b64_e32 v[70:71], v[232:233]
	v_mov_b64_e32 v[72:73], v[234:235]
	s_and_b64 vcc, exec, s[4:5]
	v_mov_b32_e32 v67, 0
	v_mov_b32_e32 v68, 0
	v_mov_b32_e32 v69, 0
	s_cbranch_vccnz .LBB0_485
	v_add_co_u32_e32 v66, vcc, 0x16000, v174
	s_nop 1
	v_addc_co_u32_e32 v67, vcc, 0, v175, vcc
	global_load_dwordx4 v[66:69], v[66:67], off

;     __device__ __forceinline__ void operator()(const f32x4 (&acc)[2][2][4][2], const Unit& u, int wr, int wc, int fr, int fq) const {
;     ...
;                     for (int bj = 0; bj < 2; ++bj) { const int m = mp * 2 + mm; const size_t off = (size_t)(row0 + ai * HALF + m * 16) * DM + col0;
;                         y[mm][bj] = *(const u32x4*)(yb + off + bj * HALF);
;                         const int slot = (ai * 4 + m) * 2 + bj;
;                         pr[mm][bj] = (u32x4){0u, 0u, 0u, 0u};
;                         if (b > 0) pr[mm][bj] = sc[(size_t)slot * NTHR]; }
.LBB0_501:
	s_nop 1
	v_lshlrev_b64 v[34:35], 12, v[178:179]
	s_mov_b64 s[18:19], 0xa0000
	v_lshl_add_u64 v[68:69], v[34:35], 0, s[18:19]
	v_lshl_add_u64 v[34:35], v[180:181], 0, v[68:69]
	v_mov_b64_e32 v[58:59], v[198:199]
	v_mov_b64_e32 v[60:61], v[200:201]
	v_mov_b32_e32 v50, 0
	s_and_b64 vcc, exec, s[4:5]
	v_mov_b32_e32 v62, 0
	v_mov_b32_e32 v63, 0
	v_mov_b32_e32 v64, 0
	v_mov_b32_e32 v65, 0
	s_cbranch_vccnz .LBB0_503
	v_add_co_u32_e32 v36, vcc, 0x18000, v174
	s_nop 1
	v_addc_co_u32_e32 v37, vcc, 0, v175, vcc
	global_load_dwordx4 v[62:65], v[36:37], off
.LBB0_503:
	v_mov_b64_e32 v[54:55], v[202:203]
	v_mov_b64_e32 v[56:57], v[204:205]
	s_and_b64 vcc, exec, s[4:5]
	v_mov_b32_e32 v51, 0
	v_mov_b32_e32 v52, 0
	v_mov_b32_e32 v53, 0
	s_cbranch_vccnz .LBB0_505
	v_add_co_u32_e32 v34, vcc, 0x1a000, v174
	s_nop 1
	v_addc_co_u32_e32 v35, vcc, 0, v175, vcc
	global_load_dwordx4 v[50:53], v[34:35], off
.LBB0_505:
	v_lshlrev_b64 v[34:35], 12, v[178:179]
	s_mov_b64 s[18:19], 0xb0000
	v_lshl_add_u64 v[66:67], v[34:35], 0, s[18:19]
	v_lshl_add_u64 v[36:37], v[180:181], 0, v[66:67]
	v_mov_b64_e32 v[42:43], v[206:207]
	v_mov_b64_e32 v[44:45], v[208:209]
	v_mov_b32_e32 v34, 0
	s_and_b64 vcc, exec, s[4:5]
	v_mov_b32_e32 v46, 0
	v_mov_b32_e32 v47, 0
	v_mov_b32_e32 v48, 0
	v_mov_b32_e32 v49, 0
	s_cbranch_vccnz .LBB0_507
	v_add_co_u32_e32 v38, vcc, 0x1c000, v174
	s_nop 1
	v_addc_co_u32_e32 v39, vcc, 0, v175, vcc
	global_load_dwordx4 v[46:49], v[38:39], off
.LBB0_507:
	s_nop 0
	v_mov_b64_e32 v[38:39], v[210:211]
	v_mov_b64_e32 v[40:41], v[212:213]
	s_and_b64 vcc, exec, s[4:5]
	v_mov_b32_e32 v35, 0
	v_mov_b32_e32 v36, 0
	v_mov_b32_e32 v37, 0
	s_cbranch_vccnz .LBB0_509
	v_add_co_u32_e32 v34, vcc, 0x1e000, v174
	s_nop 1
	v_addc_co_u32_e32 v35, vcc, 0, v175, vcc
	global_load_dwordx4 v[34:37], v[34:35], off
